# V^T copy loop: next tile's row load issued before the current tile's store so the loop wait no longer drains the store (vmcnt 1)
# baseline (speedup 1.0000x reference)
.LBB0_327:
	s_mov_b64 s[4:5], 0x8b89000
	v_lshl_add_u64 v[18:19], v[46:47], 0, s[4:5]
	v_readlane_b32 s4, v254, 6
	v_readlane_b32 s5, v254, 7
	v_lshl_add_u32 v8, s18, 6, v136
	s_andn2_b64 vcc, exec, s[4:5]
	s_waitcnt lgkmcnt(0)
	s_barrier
	s_cbranch_vccnz .LBB0_330
	v_ashrrev_i32_e32 v7, 3, v8
	v_lshlrev_b32_e32 v5, 2, v7
	s_mov_b64 s[4:5], 0x6b89000
	v_lshlrev_b32_e32 v6, 3, v136
	v_lshlrev_b32_e32 v4, 1, v7
	v_and_b32_e32 v5, 16, v5
	v_lshl_add_u64 v[2:3], v[46:47], 0, s[4:5]
	v_and_b32_e32 v0, 56, v6
	v_add_u32_e32 v5, 0, v5
	v_and_b32_e32 v4, 0xffffffe6, v4
	v_and_b32_e32 v9, 8, v7
	s_movk_i32 s4, 0x90
	v_add3_u32 v12, v5, v4, v9
	v_mul_lo_u32 v4, v7, s4
	v_lshlrev_b32_e32 v5, 1, v0
	v_add3_u32 v9, 0, v4, v5
	v_bfe_u32 v11, v6, 4, 2
	v_lshlrev_b32_e32 v4, 4, v7
	v_and_b32_e32 v6, 8, v6
	v_mul_u32_u24_e32 v13, 0x90, v0
	v_readlane_b32 s4, v254, 53
	v_readlane_b32 s5, v254, 10
	v_ashrrev_i32_e32 v5, 31, v4
	v_add_u32_e32 v10, s4, v7
	s_lshl_b32 s4, s42, 6
	v_add_u32_e32 v11, s5, v11
	s_lshl_b32 s5, s42, 2
	v_lshlrev_b32_e32 v0, 1, v0
	v_add_u32_e32 v12, v12, v13
	v_lshlrev_b32_e32 v6, 1, v6
	s_mov_b32 s6, s2
	s_ashr_i32 s7, s6, 31
	s_lshr_b32 s8, s7, 23
	s_lshr_b32 s7, s7, 26
	s_add_i32 s8, s6, s8
	s_add_i32 s7, s6, s7
	s_ashr_i32 s14, s8, 9
	s_ashr_i32 s7, s7, 6
	s_lshr_b32 s8, s7, 29
	s_lshl_b32 s9, s14, 7
	s_lshl_b32 s10, s14, 6
	s_add_i32 s8, s7, s8
	s_and_b32 s9, s9, 0xffffff00
	s_and_b32 s10, s10, 64
	s_and_b32 s8, s8, -8
	s_or_b32 s9, s9, s10
	s_sub_i32 s8, s7, s8
	s_addk_i32 s9, 0x380
	s_cmpk_lt_i32 s6, 0x800
	s_cselect_b32 s10, s9, 0x740
	s_ashr_i32 s9, s8, 31
	s_lshl_b64 s[12:13], s[8:9], 12
	s_lshl_b32 s9, s7, 12
	v_subrev_u32_e32 v14, s9, v10
	v_ashrrev_i32_e32 v15, 31, v14
	v_lshl_add_u64 v[14:15], s[12:13], 0, v[14:15]
	v_mad_u64_u32 v[16:17], s[12:13], v14, s61, v[18:19]
	s_ashr_i32 s11, s10, 31
	v_mad_i32_i24 v17, v15, s61, v17
	v_lshl_add_u64 v[14:15], s[10:11], 1, v[16:17]
	v_lshl_add_u64 v[14:15], v[14:15], 0, v[0:1]
	global_load_dwordx4 v[24:27], v[14:15], off
	s_waitcnt vmcnt(0) lgkmcnt(0)
.LBB0_329:
	s_ashr_i32 s7, s6, 31
	s_lshr_b32 s8, s7, 23
	s_lshr_b32 s7, s7, 26
	s_add_i32 s8, s6, s8
	s_add_i32 s7, s6, s7
	s_ashr_i32 s14, s8, 9
	s_ashr_i32 s7, s7, 6
	s_lshr_b32 s8, s7, 29
	s_lshl_b32 s9, s14, 7
	s_lshl_b32 s10, s14, 6
	s_add_i32 s8, s7, s8
	s_and_b32 s9, s9, 0xffffff00
	s_and_b32 s10, s10, 64
	s_and_b32 s8, s8, -8
	s_or_b32 s9, s9, s10
	s_sub_i32 s8, s7, s8
	s_addk_i32 s9, 0x380
	s_cmpk_lt_i32 s6, 0x800
	s_cselect_b32 s10, s9, 0x740
	s_ashr_i32 s9, s8, 31
	s_lshl_b64 s[12:13], s[8:9], 12
	s_lshl_b32 s9, s7, 12
	s_lshl_b32 s9, s14, 3
	s_add_i32 s8, s9, s8
	s_lshl_b32 s7, s7, 8
	s_ashr_i32 s9, s8, 31
	v_subrev_u32_e32 v22, s7, v11
	s_lshl_b64 s[8:9], s[8:9], 19
	v_ashrrev_i32_e32 v23, 31, v22
	v_lshl_add_u64 v[20:21], v[2:3], 0, s[8:9]
	v_lshlrev_b64 v[22:23], 11, v[22:23]
	v_lshl_add_u64 v[20:21], v[20:21], 0, v[22:23]
	v_lshl_add_u64 v[20:21], v[4:5], 1, v[20:21]
	v_mov_b32_e32 v7, v1
	v_lshl_add_u64 v[20:21], v[20:21], 0, v[6:7]
	s_add_i32 s6, s6, s42
	v_add_u32_e32 v10, s4, v10
	v_add_u32_e32 v11, s5, v11
	ds_write_b16 v12, v24
	ds_write_b16_d16_hi v12, v24 offset:144
	ds_write_b16 v12, v25 offset:288
	ds_write_b16_d16_hi v12, v25 offset:432
	ds_write_b16 v12, v26 offset:576
	ds_write_b16_d16_hi v12, v26 offset:720
	ds_write_b16 v12, v27 offset:864
	ds_write_b16_d16_hi v12, v27 offset:1008
	s_waitcnt lgkmcnt(0)
	s_barrier
	s_cmpk_gt_i32 s6, 0x9ff
	s_cbranch_scc1 .Lvt2_nold
	s_ashr_i32 s7, s6, 31
	s_lshr_b32 s8, s7, 23
	s_lshr_b32 s7, s7, 26
	s_add_i32 s8, s6, s8
	s_add_i32 s7, s6, s7
	s_ashr_i32 s14, s8, 9
	s_ashr_i32 s7, s7, 6
	s_lshr_b32 s8, s7, 29
	s_lshl_b32 s9, s14, 7
	s_lshl_b32 s10, s14, 6
	s_add_i32 s8, s7, s8
	s_and_b32 s9, s9, 0xffffff00
	s_and_b32 s10, s10, 64
	s_and_b32 s8, s8, -8
	s_or_b32 s9, s9, s10
	s_sub_i32 s8, s7, s8
	s_addk_i32 s9, 0x380
	s_cmpk_lt_i32 s6, 0x800
	s_cselect_b32 s10, s9, 0x740
	s_ashr_i32 s9, s8, 31
	s_lshl_b64 s[12:13], s[8:9], 12
	s_lshl_b32 s9, s7, 12
	v_subrev_u32_e32 v14, s9, v10
	v_ashrrev_i32_e32 v15, 31, v14
	v_lshl_add_u64 v[14:15], s[12:13], 0, v[14:15]
	v_mad_u64_u32 v[16:17], s[12:13], v14, s61, v[18:19]
	s_ashr_i32 s11, s10, 31
	v_mad_i32_i24 v17, v15, s61, v17
	v_lshl_add_u64 v[14:15], s[10:11], 1, v[16:17]
	v_lshl_add_u64 v[14:15], v[14:15], 0, v[0:1]
	global_load_dwordx4 v[24:27], v[14:15], off
.Lvt2_nold:
	ds_read_b128 v[14:17], v9
	s_waitcnt lgkmcnt(0)
	global_store_dwordx4 v[20:21], v[14:17], off
	s_barrier
	s_cmpk_gt_i32 s6, 0x9ff
	s_cbranch_scc1 .LBB0_330
	s_waitcnt vmcnt(1)
	s_branch .LBB0_329
